# same as the previous version but the static s_setprio 1 goes to waves 0-3 (mirror experiment)
# baseline (speedup 1.0000x reference)
; __device__ __forceinline__ int otid_full() { int t = threadIdx.x; asm volatile("" : "+v"(t)); return t; }
; #define G8_LAS __attribute__((address_space(3)))
; #define G8_STAGE(bufoff, gbase, voff) do { _Pragma("unroll") for (int _i = 0; _i < 2; ++_i) \
;     __builtin_amdgcn_global_load_lds((const unsigned*)((const char*)(gbase) + (voff)[_i]), (G8_LAS unsigned*)(lds + (bufoff) + ldsw + _i * 8192), 16, 0, 0); } while (0)
; #define G8_WAIT_V(n) asm volatile("s_waitcnt vmcnt(" #n ")" ::: "memory")
; #define G8_BAR __builtin_amdgcn_s_barrier()
; __device__ __forceinline__ void gemm256(const bf* __restrict__ A, int lda, const bf* __restrict__ Bt, int ldb, int K,
;                                         int brow, int bcol, f32x4 (&acc)[2][2][4][2]) {
;   G8_LAS unsigned char* lds = (G8_LAS unsigned char*)dynsm;
;   const int tid = otid_full(), wid = __builtin_amdgcn_readfirstlane(tid >> 6), lane = tid & 63, wr = wid >> 2, wc = wid & 3, fr = lane & 15, fq = lane >> 4;
;   unsigned voffA[2], voffB[2];
; #pragma unroll
;   for (int i = 0; i < 2; ++i) { int R, C; g8_stage_rc(tid * 16 + i * 8192, R, C); voffA[i] = (unsigned)(R * lda + C) * 2u; voffB[i] = (unsigned)(R * ldb + C) * 2u; }
;   const size_t kstep = 128;
;   const size_t hstepA = (size_t)128 * lda * 2, hstepB = (size_t)128 * ldb * 2;
;   const unsigned ldsw = (unsigned)wid * 1024u;
;   const int aoff = g8_lds_byte(wr * 64 + fr, fq * 8), boff = g8_lds_byte(wc * 32 + fr, fq * 8);
;   const char* cA = (const char*)A + (size_t)brow * lda * 2; const char* cB = (const char*)Bt + (size_t)bcol * ldb * 2;
;   bf16x8 At[4][2], B0[2][2], B1[2][2];
;   const int nt = K / 64;
;   __syncthreads();
;   G8_STAGE(G8_OSB(0, 0), cB, voffB); G8_STAGE(G8_OSA(0, 0), cA, voffA); G8_STAGE(G8_OSB(0, 1), cB + hstepB, voffB); G8_STAGE(G8_OSA(0, 1), cA + hstepA, voffA);
;   if (wr == 1) G8_BAR;
;   G8_WAIT_V(4); G8_BAR;
;   G8_STAGE(G8_OSB(1, 0), cB + kstep, voffB); G8_STAGE(G8_OSA(1, 0), cA + kstep, voffA); G8_STAGE(G8_OSB(1, 1), cB + hstepB + kstep, voffB);
;   G8_WAIT_V(6); G8_BAR;
; __device__ __forceinline__ void phaseA(const Params& p, int layer) {
;     ...
;       const int t8 = L - nA; const int ly = t8 >> 2, tm = (t8 >> 1) & 1, tn = t8 & 1;
;       gemm256(p.memb, 2048, p.WmemT + (size_t)ly * 512 * 2048, 2048, 2048, tm * 256, tn * 256, acc);
.LBB0_204:
	v_and_b32_e32 v16, 15, v15
	v_and_b32_e32 v17, 48, v15
	v_lshlrev_b32_e32 v15, 2, v15
	v_lshlrev_b32_e32 v16, 6, v16
	v_and_b32_e32 v15, 32, v15
	s_lshl_b32 s18, s18, 12
	v_or_b32_e32 v18, v16, v17
	v_bitop3_b32 v16, v16, v15, v17 bitop3:0x36
	s_lshl_b32 s17, s17, 13
	s_and_b32 s18, s18, 0x3000
	v_or_b32_e32 v139, s18, v16
	v_bitop3_b32 v15, v18, s17, v15 bitop3:0xde
	s_lshr_b32 s18, s37, 2
	s_mov_b32 s19, s69
	s_lshl_b32 s17, s36, 12
	s_add_i32 m0, s8, 0x18000
	v_lshl_add_u64 v[8:9], v[8:9], 0, s[50:51]
	s_and_b32 s22, s38, 0x100000
	s_lshl_b64 s[20:21], s[18:19], 21
	s_and_b32 s19, s17, 0x100000
	s_waitcnt vmcnt(4)
	s_barrier
	global_load_lds_dwordx4 v[8:9], off
	v_lshl_add_u64 v[6:7], v[6:7], 0, s[50:51]
	s_add_i32 m0, s8, 0x1a000
	s_add_i32 s17, s8, 0x8000
	s_add_i32 s18, s8, 0xa000
	global_load_lds_dwordx4 v[6:7], off
	v_lshl_add_u64 v[4:5], v[4:5], 0, s[50:51]
	s_mov_b32 m0, s17
	s_add_u32 s2, s2, 0x80080
	global_load_lds_dwordx4 v[4:5], off
	v_lshl_add_u64 v[2:3], v[2:3], 0, s[50:51]
	s_mov_b32 m0, s18
	s_addc_u32 s3, s3, 0
	global_load_lds_dwordx4 v[2:3], off
	s_add_i32 m0, s8, 0x1c000
	v_lshl_add_u64 v[2:3], s[2:3], 0, v[144:145]
	global_load_lds_dwordx4 v[2:3], off
	v_lshl_add_u64 v[2:3], s[2:3], 0, v[154:155]
	s_add_i32 m0, s8, 0x1e000
	v_lshlrev_b32_e32 v4, 15, v1
	global_load_lds_dwordx4 v[2:3], off
	v_lshlrev_b32_e32 v2, 15, v10
	v_and_b32_e32 v2, 0xffff0000, v2
	v_readlane_b32 s52, v253, 3
	v_and_b32_e32 v4, 0xffff0000, v4
	v_lshl_add_u32 v2, v13, 12, v2
	v_and_b32_e32 v3, 1, v10
	v_readlane_b32 s58, v253, 9
	v_lshl_add_u32 v4, v11, 12, v4
	v_and_b32_e32 v1, 1, v1
	v_lshl_or_b32 v2, v3, 6, v2
	v_readlane_b32 s59, v253, 10
	s_add_u32 s2, s58, s22
	v_lshl_or_b32 v1, v1, 6, v4
	v_lshl_add_u32 v2, v14, 1, v2
	v_mov_b32_e32 v3, v145
	s_addc_u32 s3, s59, 0
	v_lshl_add_u32 v4, v12, 1, v1
	v_mov_b32_e32 v5, v145
	v_readlane_b32 s56, v253, 7
	v_lshl_add_u64 v[156:157], s[2:3], 0, v[2:3]
	v_lshl_add_u64 v[158:159], s[2:3], 0, v[4:5]
	s_or_b32 s2, s20, s19
	s_waitcnt vmcnt(6)
	v_readlane_b32 s57, v253, 8
	s_add_u32 s2, s56, s2
	s_addc_u32 s3, s57, s21
	v_lshl_add_u64 v[160:161], s[2:3], 0, v[2:3]
	v_lshl_add_u64 v[162:163], s[2:3], 0, v[4:5]
	s_mov_b32 s19, -2
	s_mov_b64 s[2:3], 0
	v_add_u32_e32 v1, 0, v15
	v_mov_b32_e32 v2, v0
	v_mov_b32_e32 v3, v0
	v_mov_b32_e32 v4, v0
	v_mov_b32_e32 v5, v0
	v_mov_b32_e32 v6, v0
	v_mov_b32_e32 v7, v0
	v_mov_b32_e32 v8, v0
	v_mov_b32_e32 v9, v0
	v_mov_b32_e32 v10, v0
	v_mov_b32_e32 v11, v0
	v_mov_b32_e32 v12, v0
	v_mov_b32_e32 v13, v0
	v_mov_b32_e32 v14, v0
	v_mov_b32_e32 v15, v0
	v_mov_b32_e32 v16, v0
	v_mov_b32_e32 v17, v0
	v_mov_b32_e32 v18, v0
	v_mov_b32_e32 v19, v0
	v_mov_b32_e32 v20, v0
	v_mov_b32_e32 v21, v0
	v_mov_b32_e32 v22, v0
	v_mov_b32_e32 v23, v0
	v_mov_b32_e32 v24, v0
	v_mov_b32_e32 v25, v0
	v_mov_b32_e32 v26, v0
	v_mov_b32_e32 v27, v0
	v_mov_b32_e32 v28, v0
	v_mov_b32_e32 v29, v0
	v_mov_b32_e32 v30, v0
	v_mov_b32_e32 v31, v0
	v_mov_b32_e32 v32, v0
	v_mov_b32_e32 v33, v0
	v_mov_b32_e32 v34, v0
	v_mov_b32_e32 v35, v0
	v_mov_b32_e32 v36, v0
	v_mov_b32_e32 v37, v0
	v_mov_b32_e32 v38, v0
	v_mov_b32_e32 v39, v0
	v_mov_b32_e32 v40, v0
	v_mov_b32_e32 v41, v0
	v_mov_b32_e32 v42, v0
	v_mov_b32_e32 v43, v0
	v_mov_b32_e32 v44, v0
	v_mov_b32_e32 v45, v0
	v_mov_b32_e32 v46, v0
	v_mov_b32_e32 v47, v0
	v_mov_b32_e32 v48, v0
	v_mov_b32_e32 v49, v0
	v_mov_b32_e32 v50, v0
	v_mov_b32_e32 v51, v0
	v_mov_b32_e32 v52, v0
	v_mov_b32_e32 v53, v0
	v_mov_b32_e32 v54, v0
	v_mov_b32_e32 v55, v0
	v_mov_b32_e32 v56, v0
	v_mov_b32_e32 v57, v0
	v_mov_b32_e32 v58, v0
	v_mov_b32_e32 v59, v0
	v_mov_b32_e32 v60, v0
	v_mov_b32_e32 v61, v0
	v_mov_b32_e32 v62, v0
	v_mov_b32_e32 v63, v0
	v_mov_b32_e32 v64, v0
	v_mov_b32_e32 v65, v0
	v_mov_b32_e32 v66, v0
	v_mov_b32_e32 v67, v0
	v_mov_b32_e32 v68, v0
	v_mov_b32_e32 v69, v0
	v_mov_b32_e32 v70, v0
	v_mov_b32_e32 v71, v0
	v_mov_b32_e32 v72, v0
	v_mov_b32_e32 v73, v0
	v_mov_b32_e32 v74, v0
	v_mov_b32_e32 v75, v0
	v_mov_b32_e32 v76, v0
	v_mov_b32_e32 v77, v0
	v_mov_b32_e32 v78, v0
	v_mov_b32_e32 v79, v0
	v_mov_b32_e32 v80, v0
	v_mov_b32_e32 v81, v0
	v_mov_b32_e32 v82, v0
	v_mov_b32_e32 v83, v0
	v_mov_b32_e32 v84, v0
	v_mov_b32_e32 v85, v0
	v_mov_b32_e32 v86, v0
	v_mov_b32_e32 v87, v0
	v_mov_b32_e32 v88, v0
	v_mov_b32_e32 v89, v0
	v_mov_b32_e32 v90, v0
	v_mov_b32_e32 v91, v0
	v_mov_b32_e32 v92, v0
	v_mov_b32_e32 v93, v0
	v_mov_b32_e32 v94, v0
	v_mov_b32_e32 v95, v0
	v_mov_b32_e32 v96, v0
	v_mov_b32_e32 v97, v0
	v_mov_b32_e32 v98, v0
	v_mov_b32_e32 v99, v0
	v_mov_b32_e32 v100, v0
	v_mov_b32_e32 v101, v0
	v_mov_b32_e32 v102, v0
	v_mov_b32_e32 v103, v0
	v_mov_b32_e32 v104, v0
	v_mov_b32_e32 v105, v0
	v_mov_b32_e32 v106, v0
	v_mov_b32_e32 v107, v0
	v_mov_b32_e32 v108, v0
	v_mov_b32_e32 v109, v0
	v_mov_b32_e32 v110, v0
	v_mov_b32_e32 v111, v0
	v_mov_b32_e32 v112, v0
	v_mov_b32_e32 v113, v0
	v_mov_b32_e32 v114, v0
	v_mov_b32_e32 v115, v0
	v_mov_b32_e32 v116, v0
	v_mov_b32_e32 v117, v0
	v_mov_b32_e32 v118, v0
	v_mov_b32_e32 v119, v0
	v_mov_b32_e32 v120, v0
	v_mov_b32_e32 v121, v0
	v_mov_b32_e32 v122, v0
	v_mov_b32_e32 v123, v0
	v_mov_b32_e32 v124, v0
	v_mov_b32_e32 v125, v0
	v_mov_b32_e32 v126, v0
	v_mov_b32_e32 v127, v0
	v_mov_b32_e32 v128, v0
	v_mov_b32_e32 v129, v0
	s_barrier
	v_readlane_b32 s53, v253, 4
	v_readlane_b32 s54, v253, 5
	v_readlane_b32 s55, v253, 6
	v_readlane_b32 s60, v253, 11
	v_readlane_b32 s61, v253, 12
	v_readlane_b32 s62, v253, 13
	v_readlane_b32 s63, v253, 14
	v_readlane_b32 s64, v253, 15
	v_readlane_b32 s65, v253, 16
	v_readlane_b32 s66, v253, 17
	v_readlane_b32 s67, v253, 18
	s_setprio 0
	s_bitcmp1_b32 s6, 8
	s_cbranch_scc1 .Lprio_3
	s_setprio 1

; __device__ __forceinline__ int otid_full() { int t = threadIdx.x; asm volatile("" : "+v"(t)); return t; }
; #define G8_LAS __attribute__((address_space(3)))
; #define G8_STAGE(bufoff, gbase, voff) do { _Pragma("unroll") for (int _i = 0; _i < 2; ++_i) \
;     __builtin_amdgcn_global_load_lds((const unsigned*)((const char*)(gbase) + (voff)[_i]), (G8_LAS unsigned*)(lds + (bufoff) + ldsw + _i * 8192), 16, 0, 0); } while (0)
; #define G8_WAIT_V(n) asm volatile("s_waitcnt vmcnt(" #n ")" ::: "memory")
; #define G8_BAR __builtin_amdgcn_s_barrier()
; __device__ __forceinline__ void gemm256(const bf* __restrict__ A, int lda, const bf* __restrict__ Bt, int ldb, int K,
;                                         int brow, int bcol, f32x4 (&acc)[2][2][4][2]) {
;   G8_LAS unsigned char* lds = (G8_LAS unsigned char*)dynsm;
;   const int tid = otid_full(), wid = __builtin_amdgcn_readfirstlane(tid >> 6), lane = tid & 63, wr = wid >> 2, wc = wid & 3, fr = lane & 15, fq = lane >> 4;
;   unsigned voffA[2], voffB[2];
; #pragma unroll
;   for (int i = 0; i < 2; ++i) { int R, C; g8_stage_rc(tid * 16 + i * 8192, R, C); voffA[i] = (unsigned)(R * lda + C) * 2u; voffB[i] = (unsigned)(R * ldb + C) * 2u; }
;   const size_t kstep = 128;
;   const size_t hstepA = (size_t)128 * lda * 2, hstepB = (size_t)128 * ldb * 2;
;   const unsigned ldsw = (unsigned)wid * 1024u;
;   const int aoff = g8_lds_byte(wr * 64 + fr, fq * 8), boff = g8_lds_byte(wc * 32 + fr, fq * 8);
;   const char* cA = (const char*)A + (size_t)brow * lda * 2; const char* cB = (const char*)Bt + (size_t)bcol * ldb * 2;
;   bf16x8 At[4][2], B0[2][2], B1[2][2];
;   const int nt = K / 64;
;   __syncthreads();
;   G8_STAGE(G8_OSB(0, 0), cB, voffB); G8_STAGE(G8_OSA(0, 0), cA, voffA); G8_STAGE(G8_OSB(0, 1), cB + hstepB, voffB); G8_STAGE(G8_OSA(0, 1), cA + hstepA, voffA);
;   if (wr == 1) G8_BAR;
;   G8_WAIT_V(4); G8_BAR;
;   G8_STAGE(G8_OSB(1, 0), cB + kstep, voffB); G8_STAGE(G8_OSA(1, 0), cA + kstep, voffA); G8_STAGE(G8_OSB(1, 1), cB + hstepB + kstep, voffB);
;   G8_WAIT_V(6); G8_BAR;
; __device__ __forceinline__ void phaseA(const Params& p, int layer) {
;     ...
;       int pm, pn; tile_order(L, 128, 23, pm, pn);
;       const int brow = pm * 256, bcol = pn * 256;
;       gemm256(p.xb, 2048, Wl, 2048, 2048, brow, bcol, acc);
.LBB0_276:
	v_and_b32_e32 v16, 15, v15
	v_and_b32_e32 v17, 48, v15
	v_lshlrev_b32_e32 v15, 2, v15
	v_lshlrev_b32_e32 v16, 6, v16
	v_and_b32_e32 v15, 32, v15
	s_lshl_b32 s22, s22, 12
	v_or_b32_e32 v18, v16, v17
	v_bitop3_b32 v16, v16, v15, v17 bitop3:0x36
	s_lshl_b32 s21, s21, 13
	s_and_b32 s22, s22, 0x3000
	s_add_i32 m0, s1, 0x18000
	v_lshl_add_u64 v[8:9], v[8:9], 0, s[50:51]
	v_or_b32_e32 v141, s22, v16
	v_bitop3_b32 v15, v18, s21, v15 bitop3:0xde
	s_waitcnt vmcnt(4)
	s_barrier
	global_load_lds_dwordx4 v[8:9], off
	v_lshl_add_u64 v[6:7], v[6:7], 0, s[50:51]
	s_add_i32 m0, s1, 0x1a000
	s_add_i32 s21, s1, 0x8000
	s_add_i32 s22, s1, 0xa000
	global_load_lds_dwordx4 v[6:7], off
	v_lshl_add_u64 v[4:5], v[4:5], 0, s[50:51]
	s_mov_b32 m0, s21
	s_add_u32 s8, s8, 0x80080
	global_load_lds_dwordx4 v[4:5], off
	v_lshl_add_u64 v[2:3], v[2:3], 0, s[50:51]
	s_mov_b32 m0, s22
	s_addc_u32 s9, s9, 0
	global_load_lds_dwordx4 v[2:3], off
	s_add_i32 m0, s1, 0x1c000
	v_lshl_add_u64 v[2:3], s[8:9], 0, v[144:145]
	global_load_lds_dwordx4 v[2:3], off
	v_lshl_add_u64 v[2:3], s[8:9], 0, v[128:129]
	s_add_i32 m0, s1, 0x1e000
	s_sub_i32 s9, s23, s42
	global_load_lds_dwordx4 v[2:3], off
	s_sub_i32 s9, s9, s41
	s_sext_i32_i16 s9, s9
	s_lshl_b32 s8, s40, 11
	s_lshl_b32 s9, s9, 8
	s_add_i32 s8, s8, s9
	s_ashr_i32 s9, s8, 31
	v_readlane_b32 s52, v253, 3
	s_lshl_b64 s[8:9], s[8:9], 12
	v_lshlrev_b32_e32 v2, 15, v10
	v_readlane_b32 s60, v253, 11
	v_lshlrev_b32_e32 v4, 15, v1
	v_and_b32_e32 v2, 0xffff0000, v2
	v_readlane_b32 s61, v253, 12
	s_add_u32 s8, s60, s8
	v_and_b32_e32 v4, 0xffff0000, v4
	v_lshl_add_u32 v2, v13, 12, v2
	v_and_b32_e32 v3, 1, v10
	s_addc_u32 s9, s61, s9
	v_lshl_add_u32 v4, v11, 12, v4
	v_and_b32_e32 v1, 1, v1
	s_waitcnt vmcnt(6)
	v_lshl_or_b32 v2, v3, 6, v2
	v_lshl_or_b32 v1, v1, 6, v4
	s_add_u32 s6, s29, s6
	v_lshl_add_u32 v2, v14, 1, v2
	v_mov_b32_e32 v3, v145
	v_lshl_add_u32 v4, v12, 1, v1
	v_mov_b32_e32 v5, v145
	s_addc_u32 s7, s30, s7
	v_lshl_add_u64 v[154:155], s[8:9], 0, v[2:3]
	v_lshl_add_u64 v[156:157], s[8:9], 0, v[4:5]
	v_lshl_add_u64 v[158:159], s[6:7], 0, v[2:3]
	v_lshl_add_u64 v[160:161], s[6:7], 0, v[4:5]
	s_mov_b32 s8, -2
	s_mov_b64 s[6:7], 0
	v_add_u32_e32 v139, 0, v15
	v_mov_b32_e32 v1, v0
	v_mov_b32_e32 v2, v0
	v_mov_b32_e32 v3, v0
	v_mov_b32_e32 v4, v0
	v_mov_b32_e32 v5, v0
	v_mov_b32_e32 v6, v0
	v_mov_b32_e32 v7, v0
	v_mov_b32_e32 v8, v0
	v_mov_b32_e32 v9, v0
	v_mov_b32_e32 v10, v0
	v_mov_b32_e32 v11, v0
	v_mov_b32_e32 v12, v0
	v_mov_b32_e32 v13, v0
	v_mov_b32_e32 v14, v0
	v_mov_b32_e32 v15, v0
	v_mov_b32_e32 v16, v0
	v_mov_b32_e32 v17, v0
	v_mov_b32_e32 v18, v0
	v_mov_b32_e32 v19, v0
	v_mov_b32_e32 v20, v0
	v_mov_b32_e32 v21, v0
	v_mov_b32_e32 v22, v0
	v_mov_b32_e32 v23, v0
	v_mov_b32_e32 v24, v0
	v_mov_b32_e32 v25, v0
	v_mov_b32_e32 v26, v0
	v_mov_b32_e32 v27, v0
	v_mov_b32_e32 v28, v0
	v_mov_b32_e32 v29, v0
	v_mov_b32_e32 v30, v0
	v_mov_b32_e32 v31, v0
	v_mov_b32_e32 v32, v0
	v_mov_b32_e32 v33, v0
	v_mov_b32_e32 v34, v0
	v_mov_b32_e32 v35, v0
	v_mov_b32_e32 v36, v0
	v_mov_b32_e32 v37, v0
	v_mov_b32_e32 v38, v0
	v_mov_b32_e32 v39, v0
	v_mov_b32_e32 v40, v0
	v_mov_b32_e32 v41, v0
	v_mov_b32_e32 v42, v0
	v_mov_b32_e32 v43, v0
	v_mov_b32_e32 v44, v0
	v_mov_b32_e32 v45, v0
	v_mov_b32_e32 v46, v0
	v_mov_b32_e32 v47, v0
	v_mov_b32_e32 v48, v0
	v_mov_b32_e32 v49, v0
	v_mov_b32_e32 v50, v0
	v_mov_b32_e32 v51, v0
	v_mov_b32_e32 v52, v0
	v_mov_b32_e32 v53, v0
	v_mov_b32_e32 v54, v0
	v_mov_b32_e32 v55, v0
	v_mov_b32_e32 v56, v0
	v_mov_b32_e32 v57, v0
	v_mov_b32_e32 v58, v0
	v_mov_b32_e32 v59, v0
	v_mov_b32_e32 v60, v0
	v_mov_b32_e32 v61, v0
	v_mov_b32_e32 v62, v0
	v_mov_b32_e32 v63, v0
	v_mov_b32_e32 v64, v0
	v_mov_b32_e32 v65, v0
	v_mov_b32_e32 v66, v0
	v_mov_b32_e32 v67, v0
	v_mov_b32_e32 v68, v0
	v_mov_b32_e32 v69, v0
	v_mov_b32_e32 v70, v0
	v_mov_b32_e32 v71, v0
	v_mov_b32_e32 v72, v0
	v_mov_b32_e32 v73, v0
	v_mov_b32_e32 v74, v0
	v_mov_b32_e32 v75, v0
	v_mov_b32_e32 v76, v0
	v_mov_b32_e32 v77, v0
	v_mov_b32_e32 v78, v0
	v_mov_b32_e32 v79, v0
	v_mov_b32_e32 v80, v0
	v_mov_b32_e32 v81, v0
	v_mov_b32_e32 v82, v0
	v_mov_b32_e32 v83, v0
	v_mov_b32_e32 v84, v0
	v_mov_b32_e32 v85, v0
	v_mov_b32_e32 v86, v0
	v_mov_b32_e32 v87, v0
	v_mov_b32_e32 v88, v0
	v_mov_b32_e32 v89, v0
	v_mov_b32_e32 v90, v0
	v_mov_b32_e32 v91, v0
	v_mov_b32_e32 v92, v0
	v_mov_b32_e32 v93, v0
	v_mov_b32_e32 v94, v0
	v_mov_b32_e32 v95, v0
	v_mov_b32_e32 v96, v0
	v_mov_b32_e32 v97, v0
	v_mov_b32_e32 v98, v0
	v_mov_b32_e32 v99, v0
	v_mov_b32_e32 v100, v0
	v_mov_b32_e32 v101, v0
	v_mov_b32_e32 v102, v0
	v_mov_b32_e32 v103, v0
	v_mov_b32_e32 v104, v0
	v_mov_b32_e32 v105, v0
	v_mov_b32_e32 v106, v0
	v_mov_b32_e32 v107, v0
	v_mov_b32_e32 v108, v0
	v_mov_b32_e32 v109, v0
	v_mov_b32_e32 v110, v0
	v_mov_b32_e32 v111, v0
	v_mov_b32_e32 v112, v0
	v_mov_b32_e32 v113, v0
	v_mov_b32_e32 v114, v0
	v_mov_b32_e32 v115, v0
	v_mov_b32_e32 v116, v0
	v_mov_b32_e32 v117, v0
	v_mov_b32_e32 v118, v0
	v_mov_b32_e32 v119, v0
	v_mov_b32_e32 v120, v0
	v_mov_b32_e32 v121, v0
	v_mov_b32_e32 v122, v0
	v_mov_b32_e32 v123, v0
	v_mov_b32_e32 v124, v0
	v_mov_b32_e32 v125, v0
	v_mov_b32_e32 v126, v0
	v_mov_b32_e32 v127, v0
	s_barrier
	v_readlane_b32 s53, v253, 4
	v_readlane_b32 s54, v253, 5
	v_readlane_b32 s55, v253, 6
	v_readlane_b32 s56, v253, 7
	v_readlane_b32 s57, v253, 8
	v_readlane_b32 s58, v253, 9
	v_readlane_b32 s59, v253, 10
	v_readlane_b32 s62, v253, 13
	v_readlane_b32 s63, v253, 14
	v_readlane_b32 s64, v253, 15
	v_readlane_b32 s65, v253, 16
	v_readlane_b32 s66, v253, 17
	v_readlane_b32 s67, v253, 18
	s_setprio 0
	s_bitcmp1_b32 s11, 8
	s_cbranch_scc1 .Lprio_2
	s_setprio 1

; __device__ __forceinline__ int otid_full() { int t = threadIdx.x; asm volatile("" : "+v"(t)); return t; }
; #define G8_LAS __attribute__((address_space(3)))
; #define G8_WAIT_V(n) asm volatile("s_waitcnt vmcnt(" #n ")" ::: "memory")
; __device__ __forceinline__ void gemm256(const bf* __restrict__ A, int lda, const bf* __restrict__ Bt, int ldb, int K,
;                                         int brow, int bcol, f32x4 (&acc)[2][2][4][2]) {
;   G8_LAS unsigned char* lds = (G8_LAS unsigned char*)dynsm;
;   const int tid = otid_full(), wid = __builtin_amdgcn_readfirstlane(tid >> 6), lane = tid & 63, wr = wid >> 2, wc = wid & 3, fr = lane & 15, fq = lane >> 4;
;   unsigned voffA[2], voffB[2];
; #pragma unroll
;   for (int i = 0; i < 2; ++i) { int R, C; g8_stage_rc(tid * 16 + i * 8192, R, C); voffA[i] = (unsigned)(R * lda + C) * 2u; voffB[i] = (unsigned)(R * ldb + C) * 2u; }
;   const size_t kstep = 128;
;   const size_t hstepA = (size_t)128 * lda * 2, hstepB = (size_t)128 * ldb * 2;
;   const unsigned ldsw = (unsigned)wid * 1024u;
;   const int aoff = g8_lds_byte(wr * 64 + fr, fq * 8), boff = g8_lds_byte(wc * 32 + fr, fq * 8);
;   const char* cA = (const char*)A + (size_t)brow * lda * 2; const char* cB = (const char*)Bt + (size_t)bcol * ldb * 2;
;   bf16x8 At[4][2], B0[2][2], B1[2][2];
;   const int nt = K / 64;
;   __syncthreads();
;   G8_STAGE(G8_OSB(0, 0), cB, voffB); G8_STAGE(G8_OSA(0, 0), cA, voffA); G8_STAGE(G8_OSB(0, 1), cB + hstepB, voffB); G8_STAGE(G8_OSA(0, 1), cA + hstepA, voffA);
;   if (wr == 1) G8_BAR;
;   G8_WAIT_V(4); G8_BAR;
;   G8_STAGE(G8_OSB(1, 0), cB + kstep, voffB); G8_STAGE(G8_OSA(1, 0), cA + kstep, voffA); G8_STAGE(G8_OSB(1, 1), cB + hstepB + kstep, voffB);
;   G8_WAIT_V(6); G8_BAR;
; __device__ __forceinline__ void phaseE(const Params& p, int layer) {
;     ...
;     for (int s = 0; s < 8; s++) {
;       const int br = s >> 1; const bool isBr = (s & 1) != 0;
;       const int koff = br == 0 ? 0 : (br == 1 ? 512 : (br == 2 ? 1024 : 2048));
;       const int kb = br == 2 ? 1024 : (br == 3 ? 256 : 512);
;       const bf* A_ = isBr ? p.Y + koff : p.xb; const int lda_ = isBr ? YW : 2048;
;       const bf* B_ = isBr ? Wb + koff : Wl + (size_t)(5716 + br * 2048) * 2048; const int ldb_ = isBr ? YW : 2048;
;       const int K_ = isBr ? kb : 2048;
;       f32x4 acc[2][2][4][2]; ZERO_ACC8(acc);
;       gemm256(A_, lda_, B_, ldb_, K_, brow, bcol, acc);
.LBB0_2317:
	s_cmp_eq_u32 s5, 3
	s_cselect_b32 s78, 4, 8
	s_and_b64 s[16:17], s[16:17], exec
	s_cselect_b32 s78, 16, s78
	s_and_b64 s[16:17], s[18:19], exec
	s_cselect_b32 s18, 32, s78
	s_add_i32 m0, s41, 0x18000
	v_lshl_add_u64 v[2:3], v[2:3], 0, s[50:51]
	s_waitcnt vmcnt(4)
	s_barrier
	global_load_lds_dwordx4 v[2:3], off
	v_lshl_add_u64 v[2:3], v[4:5], 0, s[50:51]
	s_add_i32 m0, s41, 0x1a000
	s_add_i32 s19, s41, 0x8000
	s_lshl_b32 s17, s46, 13
	global_load_lds_dwordx4 v[2:3], off
	v_lshl_add_u64 v[2:3], v[6:7], 0, s[50:51]
	s_mov_b32 m0, s19
	s_add_i32 s46, s41, 0xa000
	global_load_lds_dwordx4 v[2:3], off
	v_lshl_add_u64 v[2:3], v[8:9], 0, s[50:51]
	s_mov_b32 m0, s46
	v_and_b32_e32 v20, 15, v17
	global_load_lds_dwordx4 v[2:3], off
	s_add_i32 m0, s41, 0x1c000
	v_lshl_add_u64 v[2:3], v[10:11], 0, s[50:51]
	global_load_lds_dwordx4 v[2:3], off
	v_lshl_add_u64 v[2:3], v[12:13], 0, s[50:51]
	s_add_i32 m0, s41, 0x1e000
	v_and_b32_e32 v21, 48, v17
	global_load_lds_dwordx4 v[2:3], off
	v_lshlrev_b32_e32 v17, 2, v17
	v_lshlrev_b32_e32 v20, 6, v20
	v_and_b32_e32 v17, 32, v17
	s_lshl_b32 s16, s47, 12
	v_or_b32_e32 v22, v20, v21
	v_bitop3_b32 v20, v20, v17, v21 bitop3:0x36
	s_and_b32 s16, s16, 0x3000
	v_or_b32_e32 v157, s16, v20
	v_bitop3_b32 v17, v22, s17, v17 bitop3:0xde
	s_mul_i32 s16, s9, s49
	s_mul_hi_u32 s17, s8, s49
	s_add_i32 s47, s18, -2
	s_add_i32 s17, s17, s16
	s_mul_i32 s16, s8, s49
	v_add_u32_e32 v1, v15, v1
	v_add_lshl_u32 v2, v1, v14, 1
	s_add_u32 s16, s75, s16
	v_add_u32_e32 v1, v19, v16
	v_mov_b32_e32 v3, v145
	s_addc_u32 s17, s74, s17
	v_add_lshl_u32 v4, v1, v18, 1
	v_mov_b32_e32 v5, v145
	v_lshl_add_u64 v[130:131], s[16:17], 0, v[2:3]
	v_lshl_add_u64 v[132:133], s[16:17], 0, v[4:5]
	s_mul_i32 s16, s38, s49
	s_mul_hi_u32 s17, s37, s49
	s_add_i32 s17, s17, s16
	s_mul_i32 s16, s37, s49
	s_add_u32 s16, s75, s16
	s_addc_u32 s17, s74, s17
	v_lshl_add_u64 v[134:135], s[16:17], 0, v[2:3]
	v_lshl_add_u64 v[136:137], s[16:17], 0, v[4:5]
	s_add_u32 s16, s68, s77
	s_addc_u32 s17, s48, s76
	v_lshl_add_u64 v[138:139], s[16:17], 0, v[2:3]
	v_lshl_add_u64 v[140:141], s[16:17], 0, v[4:5]
	s_mul_i32 s16, s11, s49
	s_mul_hi_u32 s17, s10, s49
	s_add_i32 s17, s17, s16
	s_mul_i32 s16, s10, s49
	s_waitcnt vmcnt(6)
	s_add_u32 s16, s68, s16
	s_addc_u32 s17, s48, s17
	v_lshl_add_u64 v[142:143], s[16:17], 0, v[2:3]
	v_lshl_add_u64 v[154:155], s[16:17], 0, v[4:5]
	s_mov_b32 s48, 0
	s_mov_b64 s[16:17], 0
	v_add_u32_e32 v156, 0, v17
	v_mov_b32_e32 v1, v0
	v_mov_b32_e32 v2, v0
	v_mov_b32_e32 v3, v0
	v_mov_b32_e32 v4, v0
	v_mov_b32_e32 v5, v0
	v_mov_b32_e32 v6, v0
	v_mov_b32_e32 v7, v0
	v_mov_b32_e32 v8, v0
	v_mov_b32_e32 v9, v0
	v_mov_b32_e32 v10, v0
	v_mov_b32_e32 v11, v0
	v_mov_b32_e32 v12, v0
	v_mov_b32_e32 v13, v0
	v_mov_b32_e32 v14, v0
	v_mov_b32_e32 v15, v0
	v_mov_b32_e32 v16, v0
	v_mov_b32_e32 v17, v0
	v_mov_b32_e32 v18, v0
	v_mov_b32_e32 v19, v0
	v_mov_b32_e32 v20, v0
	v_mov_b32_e32 v21, v0
	v_mov_b32_e32 v22, v0
	v_mov_b32_e32 v23, v0
	v_mov_b32_e32 v24, v0
	v_mov_b32_e32 v25, v0
	v_mov_b32_e32 v26, v0
	v_mov_b32_e32 v27, v0
	v_mov_b32_e32 v28, v0
	v_mov_b32_e32 v29, v0
	v_mov_b32_e32 v30, v0
	v_mov_b32_e32 v31, v0
	v_mov_b32_e32 v32, v0
	v_mov_b32_e32 v33, v0
	v_mov_b32_e32 v34, v0
	v_mov_b32_e32 v35, v0
	v_mov_b32_e32 v36, v0
	v_mov_b32_e32 v37, v0
	v_mov_b32_e32 v38, v0
	v_mov_b32_e32 v39, v0
	v_mov_b32_e32 v40, v0
	v_mov_b32_e32 v41, v0
	v_mov_b32_e32 v42, v0
	v_mov_b32_e32 v43, v0
	v_mov_b32_e32 v44, v0
	v_mov_b32_e32 v45, v0
	v_mov_b32_e32 v46, v0
	v_mov_b32_e32 v47, v0
	v_mov_b32_e32 v48, v0
	v_mov_b32_e32 v49, v0
	v_mov_b32_e32 v50, v0
	v_mov_b32_e32 v51, v0
	v_mov_b32_e32 v52, v0
	v_mov_b32_e32 v53, v0
	v_mov_b32_e32 v54, v0
	v_mov_b32_e32 v55, v0
	v_mov_b32_e32 v56, v0
	v_mov_b32_e32 v57, v0
	v_mov_b32_e32 v58, v0
	v_mov_b32_e32 v59, v0
	v_mov_b32_e32 v60, v0
	v_mov_b32_e32 v61, v0
	v_mov_b32_e32 v62, v0
	v_mov_b32_e32 v63, v0
	v_mov_b32_e32 v64, v0
	v_mov_b32_e32 v65, v0
	v_mov_b32_e32 v66, v0
	v_mov_b32_e32 v67, v0
	v_mov_b32_e32 v68, v0
	v_mov_b32_e32 v69, v0
	v_mov_b32_e32 v70, v0
	v_mov_b32_e32 v71, v0
	v_mov_b32_e32 v72, v0
	v_mov_b32_e32 v73, v0
	v_mov_b32_e32 v74, v0
	v_mov_b32_e32 v75, v0
	v_mov_b32_e32 v76, v0
	v_mov_b32_e32 v77, v0
	v_mov_b32_e32 v78, v0
	v_mov_b32_e32 v79, v0
	v_mov_b32_e32 v80, v0
	v_mov_b32_e32 v81, v0
	v_mov_b32_e32 v82, v0
	v_mov_b32_e32 v83, v0
	v_mov_b32_e32 v84, v0
	v_mov_b32_e32 v85, v0
	v_mov_b32_e32 v86, v0
	v_mov_b32_e32 v87, v0
	v_mov_b32_e32 v88, v0
	v_mov_b32_e32 v89, v0
	v_mov_b32_e32 v90, v0
	v_mov_b32_e32 v91, v0
	v_mov_b32_e32 v92, v0
	v_mov_b32_e32 v93, v0
	v_mov_b32_e32 v94, v0
	v_mov_b32_e32 v95, v0
	v_mov_b32_e32 v96, v0
	v_mov_b32_e32 v97, v0
	v_mov_b32_e32 v98, v0
	v_mov_b32_e32 v99, v0
	v_mov_b32_e32 v100, v0
	v_mov_b32_e32 v101, v0
	v_mov_b32_e32 v102, v0
	v_mov_b32_e32 v103, v0
	v_mov_b32_e32 v104, v0
	v_mov_b32_e32 v105, v0
	v_mov_b32_e32 v106, v0
	v_mov_b32_e32 v107, v0
	v_mov_b32_e32 v108, v0
	v_mov_b32_e32 v109, v0
	v_mov_b32_e32 v110, v0
	v_mov_b32_e32 v111, v0
	v_mov_b32_e32 v112, v0
	v_mov_b32_e32 v113, v0
	v_mov_b32_e32 v114, v0
	v_mov_b32_e32 v115, v0
	v_mov_b32_e32 v116, v0
	v_mov_b32_e32 v117, v0
	v_mov_b32_e32 v118, v0
	v_mov_b32_e32 v119, v0
	v_mov_b32_e32 v120, v0
	v_mov_b32_e32 v121, v0
	v_mov_b32_e32 v122, v0
	v_mov_b32_e32 v123, v0
	v_mov_b32_e32 v124, v0
	v_mov_b32_e32 v125, v0
	v_mov_b32_e32 v126, v0
	v_mov_b32_e32 v127, v0
	s_barrier
	s_setprio 0
	s_bitcmp1_b32 s39, 8
	s_cbranch_scc1 .Lprio_1
	s_setprio 1

; __device__ __forceinline__ int otid_full() { int t = threadIdx.x; asm volatile("" : "+v"(t)); return t; }
; #define G8_LAS __attribute__((address_space(3)))
; #define G8_STAGE(bufoff, gbase, voff) do { _Pragma("unroll") for (int _i = 0; _i < 2; ++_i) \
;     __builtin_amdgcn_global_load_lds((const unsigned*)((const char*)(gbase) + (voff)[_i]), (G8_LAS unsigned*)(lds + (bufoff) + ldsw + _i * 8192), 16, 0, 0); } while (0)
; #define G8_WAIT_V(n) asm volatile("s_waitcnt vmcnt(" #n ")" ::: "memory")
; __device__ __forceinline__ void gemm256(const bf* __restrict__ A, int lda, const bf* __restrict__ Bt, int ldb, int K,
;                                         int brow, int bcol, f32x4 (&acc)[2][2][4][2]) {
;   G8_LAS unsigned char* lds = (G8_LAS unsigned char*)dynsm;
;   const int tid = otid_full(), wid = __builtin_amdgcn_readfirstlane(tid >> 6), lane = tid & 63, wr = wid >> 2, wc = wid & 3, fr = lane & 15, fq = lane >> 4;
;   unsigned voffA[2], voffB[2];
; #pragma unroll
;   for (int i = 0; i < 2; ++i) { int R, C; g8_stage_rc(tid * 16 + i * 8192, R, C); voffA[i] = (unsigned)(R * lda + C) * 2u; voffB[i] = (unsigned)(R * ldb + C) * 2u; }
;   const size_t kstep = 128;
;   const size_t hstepA = (size_t)128 * lda * 2, hstepB = (size_t)128 * ldb * 2;
;   const unsigned ldsw = (unsigned)wid * 1024u;
;   const int aoff = g8_lds_byte(wr * 64 + fr, fq * 8), boff = g8_lds_byte(wc * 32 + fr, fq * 8);
;   const char* cA = (const char*)A + (size_t)brow * lda * 2; const char* cB = (const char*)Bt + (size_t)bcol * ldb * 2;
;   bf16x8 At[4][2], B0[2][2], B1[2][2];
;   const int nt = K / 64;
;   __syncthreads();
;   G8_STAGE(G8_OSB(0, 0), cB, voffB); G8_STAGE(G8_OSA(0, 0), cA, voffA); G8_STAGE(G8_OSB(0, 1), cB + hstepB, voffB); G8_STAGE(G8_OSA(0, 1), cA + hstepA, voffA);
;   if (wr == 1) G8_BAR;
;   G8_WAIT_V(4); G8_BAR;
;   G8_STAGE(G8_OSB(1, 0), cB + kstep, voffB); G8_STAGE(G8_OSA(1, 0), cA + kstep, voffA); G8_STAGE(G8_OSB(1, 1), cB + hstepB + kstep, voffB);
;   G8_WAIT_V(6); G8_BAR;
; __device__ __forceinline__ void phaseF(const Params& p, int layer) {
;     ...
;   for (int L = blockIdx.x; L < 1024; L += gridDim.x) {
;     int pm, pn; tile_order(L, 128, 8, pm, pn);
;     const int brow = pm * 256, bcol = pn * 256;
;     f32x4 acc[2][2][4][2]; ZERO_ACC8(acc);
;     gemm256(merged, 2048, p.WoutT + (size_t)layer * 2048 * 2048, 2048, 2048, brow, bcol, acc);
.LBB0_2436:
	v_and_b32_e32 v16, 15, v15
	v_and_b32_e32 v17, 48, v15
	v_lshlrev_b32_e32 v15, 2, v15
	v_lshlrev_b32_e32 v16, 6, v16
	v_and_b32_e32 v15, 32, v15
	s_lshl_b32 s22, s22, 12
	v_or_b32_e32 v18, v16, v17
	v_bitop3_b32 v16, v16, v15, v17 bitop3:0x36
	s_lshl_b32 s21, s21, 13
	s_and_b32 s22, s22, 0x3000
	s_add_i32 m0, s3, 0x18000
	v_lshl_add_u64 v[8:9], v[8:9], 0, s[50:51]
	v_or_b32_e32 v141, s22, v16
	v_bitop3_b32 v15, v18, s21, v15 bitop3:0xde
	s_waitcnt vmcnt(4)
	s_barrier
	global_load_lds_dwordx4 v[8:9], off
	v_lshl_add_u64 v[6:7], v[6:7], 0, s[50:51]
	s_add_i32 m0, s3, 0x1a000
	s_add_i32 s21, s3, 0x8000
	s_add_i32 s22, s3, 0xa000
	global_load_lds_dwordx4 v[6:7], off
	v_lshl_add_u64 v[4:5], v[4:5], 0, s[50:51]
	s_mov_b32 m0, s21
	s_add_u32 s10, s10, 0x80080
	global_load_lds_dwordx4 v[4:5], off
	v_lshl_add_u64 v[2:3], v[2:3], 0, s[50:51]
	s_mov_b32 m0, s22
	s_addc_u32 s11, s11, 0
	global_load_lds_dwordx4 v[2:3], off
	s_add_i32 m0, s3, 0x1c000
	v_lshl_add_u64 v[2:3], s[10:11], 0, v[144:145]
	global_load_lds_dwordx4 v[2:3], off
	v_lshl_add_u64 v[2:3], s[10:11], 0, v[128:129]
	s_add_i32 m0, s3, 0x1e000
	s_sub_i32 s11, s23, s25
	global_load_lds_dwordx4 v[2:3], off
	s_lshl_b32 s23, s24, 6
	s_sub_i32 s11, s11, s23
	s_sext_i32_i8 s11, s11
	s_lshl_b32 s10, s24, 11
	s_lshl_b32 s11, s11, 8
	s_add_i32 s10, s10, s11
	s_ashr_i32 s11, s10, 31
	v_readlane_b32 s52, v253, 3
	s_lshl_b64 s[10:11], s[10:11], 12
	v_lshlrev_b32_e32 v2, 15, v10
	v_readlane_b32 s62, v253, 13
	v_lshlrev_b32_e32 v4, 15, v1
	v_and_b32_e32 v2, 0xffff0000, v2
	v_readlane_b32 s63, v253, 14
	s_add_u32 s10, s62, s10
	v_and_b32_e32 v4, 0xffff0000, v4
	v_lshl_add_u32 v2, v13, 12, v2
	v_and_b32_e32 v3, 1, v10
	s_addc_u32 s11, s63, s11
	v_lshl_add_u32 v4, v11, 12, v4
	v_and_b32_e32 v1, 1, v1
	s_waitcnt vmcnt(6)
	v_lshl_or_b32 v2, v3, 6, v2
	v_lshl_or_b32 v1, v1, 6, v4
	s_add_u32 s8, s14, s8
	v_lshl_add_u32 v2, v14, 1, v2
	v_mov_b32_e32 v3, v145
	v_lshl_add_u32 v4, v12, 1, v1
	v_mov_b32_e32 v5, v145
	s_addc_u32 s9, s15, s9
	v_lshl_add_u64 v[130:131], s[10:11], 0, v[2:3]
	v_lshl_add_u64 v[132:133], s[10:11], 0, v[4:5]
	v_lshl_add_u64 v[134:135], s[8:9], 0, v[2:3]
	v_lshl_add_u64 v[136:137], s[8:9], 0, v[4:5]
	s_mov_b32 s10, -2
	s_mov_b64 s[8:9], 0
	v_add_u32_e32 v140, 0, v15
	v_mov_b32_e32 v1, v0
	v_mov_b32_e32 v2, v0
	v_mov_b32_e32 v3, v0
	v_mov_b32_e32 v4, v0
	v_mov_b32_e32 v5, v0
	v_mov_b32_e32 v6, v0
	v_mov_b32_e32 v7, v0
	v_mov_b32_e32 v8, v0
	v_mov_b32_e32 v9, v0
	v_mov_b32_e32 v10, v0
	v_mov_b32_e32 v11, v0
	v_mov_b32_e32 v12, v0
	v_mov_b32_e32 v13, v0
	v_mov_b32_e32 v14, v0
	v_mov_b32_e32 v15, v0
	v_mov_b32_e32 v16, v0
	v_mov_b32_e32 v17, v0
	v_mov_b32_e32 v18, v0
	v_mov_b32_e32 v19, v0
	v_mov_b32_e32 v20, v0
	v_mov_b32_e32 v21, v0
	v_mov_b32_e32 v22, v0
	v_mov_b32_e32 v23, v0
	v_mov_b32_e32 v24, v0
	v_mov_b32_e32 v25, v0
	v_mov_b32_e32 v26, v0
	v_mov_b32_e32 v27, v0
	v_mov_b32_e32 v28, v0
	v_mov_b32_e32 v29, v0
	v_mov_b32_e32 v30, v0
	v_mov_b32_e32 v31, v0
	v_mov_b32_e32 v32, v0
	v_mov_b32_e32 v33, v0
	v_mov_b32_e32 v34, v0
	v_mov_b32_e32 v35, v0
	v_mov_b32_e32 v36, v0
	v_mov_b32_e32 v37, v0
	v_mov_b32_e32 v38, v0
	v_mov_b32_e32 v39, v0
	v_mov_b32_e32 v40, v0
	v_mov_b32_e32 v41, v0
	v_mov_b32_e32 v42, v0
	v_mov_b32_e32 v43, v0
	v_mov_b32_e32 v44, v0
	v_mov_b32_e32 v45, v0
	v_mov_b32_e32 v46, v0
	v_mov_b32_e32 v47, v0
	v_mov_b32_e32 v48, v0
	v_mov_b32_e32 v49, v0
	v_mov_b32_e32 v50, v0
	v_mov_b32_e32 v51, v0
	v_mov_b32_e32 v52, v0
	v_mov_b32_e32 v53, v0
	v_mov_b32_e32 v54, v0
	v_mov_b32_e32 v55, v0
	v_mov_b32_e32 v56, v0
	v_mov_b32_e32 v57, v0
	v_mov_b32_e32 v58, v0
	v_mov_b32_e32 v59, v0
	v_mov_b32_e32 v60, v0
	v_mov_b32_e32 v61, v0
	v_mov_b32_e32 v62, v0
	v_mov_b32_e32 v63, v0
	v_mov_b32_e32 v64, v0
	v_mov_b32_e32 v65, v0
	v_mov_b32_e32 v66, v0
	v_mov_b32_e32 v67, v0
	v_mov_b32_e32 v68, v0
	v_mov_b32_e32 v69, v0
	v_mov_b32_e32 v70, v0
	v_mov_b32_e32 v71, v0
	v_mov_b32_e32 v72, v0
	v_mov_b32_e32 v73, v0
	v_mov_b32_e32 v74, v0
	v_mov_b32_e32 v75, v0
	v_mov_b32_e32 v76, v0
	v_mov_b32_e32 v77, v0
	v_mov_b32_e32 v78, v0
	v_mov_b32_e32 v79, v0
	v_mov_b32_e32 v80, v0
	v_mov_b32_e32 v81, v0
	v_mov_b32_e32 v82, v0
	v_mov_b32_e32 v83, v0
	v_mov_b32_e32 v84, v0
	v_mov_b32_e32 v85, v0
	v_mov_b32_e32 v86, v0
	v_mov_b32_e32 v87, v0
	v_mov_b32_e32 v88, v0
	v_mov_b32_e32 v89, v0
	v_mov_b32_e32 v90, v0
	v_mov_b32_e32 v91, v0
	v_mov_b32_e32 v92, v0
	v_mov_b32_e32 v93, v0
	v_mov_b32_e32 v94, v0
	v_mov_b32_e32 v95, v0
	v_mov_b32_e32 v96, v0
	v_mov_b32_e32 v97, v0
	v_mov_b32_e32 v98, v0
	v_mov_b32_e32 v99, v0
	v_mov_b32_e32 v100, v0
	v_mov_b32_e32 v101, v0
	v_mov_b32_e32 v102, v0
	v_mov_b32_e32 v103, v0
	v_mov_b32_e32 v104, v0
	v_mov_b32_e32 v105, v0
	v_mov_b32_e32 v106, v0
	v_mov_b32_e32 v107, v0
	v_mov_b32_e32 v108, v0
	v_mov_b32_e32 v109, v0
	v_mov_b32_e32 v110, v0
	v_mov_b32_e32 v111, v0
	v_mov_b32_e32 v112, v0
	v_mov_b32_e32 v113, v0
	v_mov_b32_e32 v114, v0
	v_mov_b32_e32 v115, v0
	v_mov_b32_e32 v116, v0
	v_mov_b32_e32 v117, v0
	v_mov_b32_e32 v118, v0
	v_mov_b32_e32 v119, v0
	v_mov_b32_e32 v120, v0
	v_mov_b32_e32 v121, v0
	v_mov_b32_e32 v122, v0
	v_mov_b32_e32 v123, v0
	v_mov_b32_e32 v124, v0
	v_mov_b32_e32 v125, v0
	v_mov_b32_e32 v126, v0
	v_mov_b32_e32 v127, v0
	s_barrier
	v_readlane_b32 s53, v253, 4
	v_readlane_b32 s54, v253, 5
	v_readlane_b32 s55, v253, 6
	v_readlane_b32 s56, v253, 7
	v_readlane_b32 s57, v253, 8
	v_readlane_b32 s58, v253, 9
	v_readlane_b32 s59, v253, 10
	v_readlane_b32 s60, v253, 11
	v_readlane_b32 s61, v253, 12
	v_readlane_b32 s64, v253, 15
	v_readlane_b32 s65, v253, 16
	v_readlane_b32 s66, v253, 17
	v_readlane_b32 s67, v253, 18
	s_setprio 0
	s_bitcmp1_b32 s17, 8
	s_cbranch_scc1 .Lprio_0
	s_setprio 1
